# accumulator zeroing with 64-bit moves (64 instead of 128 per tile) on top of sigmoid-epilogue constant folding
# speedup vs baseline: 1.0000x; 1.0000x over previous
;     __device__ __forceinline__ bool next(int i, Unit& u) const { Unit t; if (!so.next(i / 3, t)) return false; const int br = i % 3; u.pm = t.pm + br * so.nM; u.pn = t.pn + br * so.nN; return true; }
;     __device__ __forceinline__ bool zero_after(const Unit& u) const { return (u.pn / nN) == 2; }
; template <class Epi, class Sched, bool ALIGN_EPI = false, bool SP2 = false>
; __device__ __forceinline__ void gemm_phase(PG8_LAS unsigned char* lds, const Gemm g, const Sched& S, const Epi& E) {
;     ...
;         const bool has_next = S.next(ui + 1, nxt);
;         const char* nA = has_next ? (const char*)g.A + (size_t)nxt.pm * tstep : cA; const char* nB = has_next ? (const char*)g.Bt + (size_t)nxt.pn * tstep : cB;
;         for (int t = 0; t < nt; t += 2) {
;     ...
;         if (E.zero_after(cur)) {
; #pragma unroll
;         for (int a = 0; a < 2; ++a)
; #pragma unroll
;             for (int b = 0; b < 2; ++b)
; #pragma unroll
;                 for (int m = 0; m < 4; ++m)
; #pragma unroll
;                     for (int n = 0; n < 2; ++n) acc[a][b][m][n] = (f32x4){0.f, 0.f, 0.f, 0.f};
;         }
.LBB0_147:
	s_ashr_i32 s25, s24, 31
	s_lshl_b64 s[26:27], s[24:25], 20
	s_add_u32 s26, s1, s26
	s_addc_u32 s27, s40, s27
	s_and_b64 s[28:29], s[4:5], exec
	s_cselect_b32 s25, s27, s7
	s_cselect_b32 s34, s26, s6
	s_ashr_i32 s23, s22, 31
	s_lshl_b64 s[28:29], s[22:23], 20
	s_add_u32 s28, s41, s28
	s_addc_u32 s29, s44, s29
	s_and_b64 s[30:31], s[4:5], exec
	s_cselect_b32 s23, s29, s9
	s_cselect_b32 s35, s28, s8
	s_add_u32 s6, s6, 0x80080
	s_addc_u32 s7, s7, 0
	s_add_u32 s36, s8, 0x100
	s_addc_u32 s37, s9, 0
	s_mov_b32 s38, -2
	v_mov_b64_e32 v[0:1], 0
	v_mov_b64_e32 v[2:3], 0
	v_mov_b64_e32 v[4:5], 0
	v_mov_b64_e32 v[6:7], 0
	v_mov_b64_e32 v[8:9], 0
	v_mov_b64_e32 v[10:11], 0
	v_mov_b64_e32 v[12:13], 0
	v_mov_b64_e32 v[14:15], 0
	v_mov_b64_e32 v[16:17], 0
	v_mov_b64_e32 v[18:19], 0
	v_mov_b64_e32 v[20:21], 0
	v_mov_b64_e32 v[22:23], 0
	v_mov_b64_e32 v[24:25], 0
	v_mov_b64_e32 v[26:27], 0
	v_mov_b64_e32 v[28:29], 0
	v_mov_b64_e32 v[30:31], 0
	v_mov_b64_e32 v[32:33], 0
	v_mov_b64_e32 v[34:35], 0
	v_mov_b64_e32 v[36:37], 0
	v_mov_b64_e32 v[38:39], 0
	v_mov_b64_e32 v[40:41], 0
	v_mov_b64_e32 v[42:43], 0
	v_mov_b64_e32 v[44:45], 0
	v_mov_b64_e32 v[46:47], 0
	v_mov_b64_e32 v[48:49], 0
	v_mov_b64_e32 v[50:51], 0
	v_mov_b64_e32 v[52:53], 0
	v_mov_b64_e32 v[54:55], 0
	v_mov_b64_e32 v[56:57], 0
	v_mov_b64_e32 v[58:59], 0
	v_mov_b64_e32 v[60:61], 0
	v_mov_b64_e32 v[62:63], 0
	v_mov_b64_e32 v[64:65], 0
	v_mov_b64_e32 v[66:67], 0
	v_mov_b64_e32 v[68:69], 0
	v_mov_b64_e32 v[70:71], 0
	v_mov_b64_e32 v[72:73], 0
	v_mov_b64_e32 v[74:75], 0
	v_mov_b64_e32 v[76:77], 0
	v_mov_b64_e32 v[78:79], 0
	v_mov_b64_e32 v[80:81], 0
	v_mov_b64_e32 v[82:83], 0
	v_mov_b64_e32 v[84:85], 0
	v_mov_b64_e32 v[86:87], 0
	v_mov_b64_e32 v[88:89], 0
	v_mov_b64_e32 v[90:91], 0
	v_mov_b64_e32 v[92:93], 0
	v_mov_b64_e32 v[94:95], 0
	v_mov_b64_e32 v[96:97], 0
	v_mov_b64_e32 v[98:99], 0
	v_mov_b64_e32 v[100:101], 0
	v_mov_b64_e32 v[102:103], 0
	v_mov_b64_e32 v[104:105], 0
	v_mov_b64_e32 v[106:107], 0
	v_mov_b64_e32 v[108:109], 0
	v_mov_b64_e32 v[110:111], 0
	v_mov_b64_e32 v[112:113], 0
	v_mov_b64_e32 v[114:115], 0
	v_mov_b64_e32 v[116:117], 0
	v_mov_b64_e32 v[118:119], 0
	v_mov_b64_e32 v[120:121], 0
	v_mov_b64_e32 v[122:123], 0
	v_mov_b64_e32 v[124:125], 0
	v_mov_b64_e32 v[126:127], 0

;     __device__ __forceinline__ bool zero_after(const Unit& u) const { return (u.pn / nN) == 2; }
; template <class Epi, class Sched, bool ALIGN_EPI = false, bool SP2 = false>
; __device__ __forceinline__ void gemm_phase(PG8_LAS unsigned char* lds, const Gemm g, const Sched& S, const Epi& E) {
;     ...
;         if (E.zero_after(cur)) {
; #pragma unroll
;         for (int a = 0; a < 2; ++a)
; #pragma unroll
;             for (int b = 0; b < 2; ++b)
; #pragma unroll
;                 for (int m = 0; m < 4; ++m)
; #pragma unroll
;                     for (int n = 0; n < 2; ++n) acc[a][b][m][n] = (f32x4){0.f, 0.f, 0.f, 0.f};
;         }
.LBB0_524:
	s_and_b32 s2, s44, -8
	s_cmp_lg_u32 s2, 16
	s_cbranch_scc1 .LBB0_526
	v_mov_b64_e32 v[0:1], 0
	v_mov_b64_e32 v[2:3], 0
	v_mov_b64_e32 v[4:5], 0
	v_mov_b64_e32 v[6:7], 0
	v_mov_b64_e32 v[8:9], 0
	v_mov_b64_e32 v[10:11], 0
	v_mov_b64_e32 v[12:13], 0
	v_mov_b64_e32 v[14:15], 0
	v_mov_b64_e32 v[16:17], 0
	v_mov_b64_e32 v[18:19], 0
	v_mov_b64_e32 v[20:21], 0
	v_mov_b64_e32 v[22:23], 0
	v_mov_b64_e32 v[24:25], 0
	v_mov_b64_e32 v[26:27], 0
	v_mov_b64_e32 v[28:29], 0
	v_mov_b64_e32 v[30:31], 0
	v_mov_b64_e32 v[32:33], 0
	v_mov_b64_e32 v[34:35], 0
	v_mov_b64_e32 v[36:37], 0
	v_mov_b64_e32 v[38:39], 0
	v_mov_b64_e32 v[40:41], 0
	v_mov_b64_e32 v[42:43], 0
	v_mov_b64_e32 v[44:45], 0
	v_mov_b64_e32 v[46:47], 0
	v_mov_b64_e32 v[48:49], 0
	v_mov_b64_e32 v[50:51], 0
	v_mov_b64_e32 v[52:53], 0
	v_mov_b64_e32 v[54:55], 0
	v_mov_b64_e32 v[56:57], 0
	v_mov_b64_e32 v[58:59], 0
	v_mov_b64_e32 v[60:61], 0
	v_mov_b64_e32 v[62:63], 0
	v_mov_b64_e32 v[64:65], 0
	v_mov_b64_e32 v[66:67], 0
	v_mov_b64_e32 v[68:69], 0
	v_mov_b64_e32 v[70:71], 0
	v_mov_b64_e32 v[72:73], 0
	v_mov_b64_e32 v[74:75], 0
	v_mov_b64_e32 v[76:77], 0
	v_mov_b64_e32 v[78:79], 0
	v_mov_b64_e32 v[80:81], 0
	v_mov_b64_e32 v[82:83], 0
	v_mov_b64_e32 v[84:85], 0
	v_mov_b64_e32 v[86:87], 0
	v_mov_b64_e32 v[88:89], 0
	v_mov_b64_e32 v[90:91], 0
	v_mov_b64_e32 v[92:93], 0
	v_mov_b64_e32 v[94:95], 0
	v_mov_b64_e32 v[96:97], 0
	v_mov_b64_e32 v[98:99], 0
	v_mov_b64_e32 v[100:101], 0
	v_mov_b64_e32 v[102:103], 0
	v_mov_b64_e32 v[104:105], 0
	v_mov_b64_e32 v[106:107], 0
	v_mov_b64_e32 v[108:109], 0
	v_mov_b64_e32 v[110:111], 0
	v_mov_b64_e32 v[112:113], 0
	v_mov_b64_e32 v[114:115], 0
	v_mov_b64_e32 v[116:117], 0
	v_mov_b64_e32 v[118:119], 0
	v_mov_b64_e32 v[120:121], 0
	v_mov_b64_e32 v[122:123], 0
	v_mov_b64_e32 v[124:125], 0
	v_mov_b64_e32 v[126:127], 0

;     __device__ __forceinline__ bool next(int i, Unit& u) const { Unit t; if (!so.next(i / 3, t)) return false; const int br = i % 3; u.pm = t.pm + br * so.nM; u.pn = t.pn + br * so.nN; return true; }
;     __device__ __forceinline__ bool zero_after(const Unit& u) const { return (u.pn / nN) == 2; }
; template <class Epi, class Sched, bool ALIGN_EPI = false, bool SP2 = false>
; __device__ __forceinline__ void gemm_phase(PG8_LAS unsigned char* lds, const Gemm g, const Sched& S, const Epi& E) {
;     ...
;         const bool has_next = S.next(ui + 1, nxt);
;         const char* nA = has_next ? (const char*)g.A + (size_t)nxt.pm * tstep : cA; const char* nB = has_next ? (const char*)g.Bt + (size_t)nxt.pn * tstep : cB;
;         for (int t = 0; t < nt; t += 2) {
;     ...
;         if (E.zero_after(cur)) {
; #pragma unroll
;         for (int a = 0; a < 2; ++a)
; #pragma unroll
;             for (int b = 0; b < 2; ++b)
; #pragma unroll
;                 for (int m = 0; m < 4; ++m)
; #pragma unroll
;                     for (int n = 0; n < 2; ++n) acc[a][b][m][n] = (f32x4){0.f, 0.f, 0.f, 0.f};
;         }
.LBB0_683:
	s_ashr_i32 s19, s18, 31
	s_lshl_b64 s[20:21], s[18:19], 20
	s_add_u32 s20, s2, s20
	s_addc_u32 s21, s28, s21
	s_and_b64 s[22:23], s[6:7], exec
	s_cselect_b32 s19, s21, s9
	s_cselect_b32 s45, s20, s8
	s_ashr_i32 s17, s16, 31
	s_lshl_b64 s[22:23], s[16:17], 20
	s_add_u32 s22, s29, s22
	s_addc_u32 s23, s30, s23
	s_and_b64 s[26:27], s[6:7], exec
	s_cselect_b32 s17, s23, s25
	s_cselect_b32 s52, s22, s24
	s_add_u32 s8, s8, 0x80080
	s_addc_u32 s9, s9, 0
	s_add_u32 s58, s24, 0x100
	s_addc_u32 s62, s25, 0
	s_mov_b32 s63, -2
	v_mov_b64_e32 v[0:1], 0
	v_mov_b64_e32 v[2:3], 0
	v_mov_b64_e32 v[4:5], 0
	v_mov_b64_e32 v[6:7], 0
	v_mov_b64_e32 v[8:9], 0
	v_mov_b64_e32 v[10:11], 0
	v_mov_b64_e32 v[12:13], 0
	v_mov_b64_e32 v[14:15], 0
	v_mov_b64_e32 v[16:17], 0
	v_mov_b64_e32 v[18:19], 0
	v_mov_b64_e32 v[20:21], 0
	v_mov_b64_e32 v[22:23], 0
	v_mov_b64_e32 v[24:25], 0
	v_mov_b64_e32 v[26:27], 0
	v_mov_b64_e32 v[28:29], 0
	v_mov_b64_e32 v[30:31], 0
	v_mov_b64_e32 v[32:33], 0
	v_mov_b64_e32 v[34:35], 0
	v_mov_b64_e32 v[36:37], 0
	v_mov_b64_e32 v[38:39], 0
	v_mov_b64_e32 v[40:41], 0
	v_mov_b64_e32 v[42:43], 0
	v_mov_b64_e32 v[44:45], 0
	v_mov_b64_e32 v[46:47], 0
	v_mov_b64_e32 v[48:49], 0
	v_mov_b64_e32 v[50:51], 0
	v_mov_b64_e32 v[52:53], 0
	v_mov_b64_e32 v[54:55], 0
	v_mov_b64_e32 v[56:57], 0
	v_mov_b64_e32 v[58:59], 0
	v_mov_b64_e32 v[60:61], 0
	v_mov_b64_e32 v[62:63], 0
	v_mov_b64_e32 v[64:65], 0
	v_mov_b64_e32 v[66:67], 0
	v_mov_b64_e32 v[68:69], 0
	v_mov_b64_e32 v[70:71], 0
	v_mov_b64_e32 v[72:73], 0
	v_mov_b64_e32 v[74:75], 0
	v_mov_b64_e32 v[76:77], 0
	v_mov_b64_e32 v[78:79], 0
	v_mov_b64_e32 v[80:81], 0
	v_mov_b64_e32 v[82:83], 0
	v_mov_b64_e32 v[84:85], 0
	v_mov_b64_e32 v[86:87], 0
	v_mov_b64_e32 v[88:89], 0
	v_mov_b64_e32 v[90:91], 0
	v_mov_b64_e32 v[92:93], 0
	v_mov_b64_e32 v[94:95], 0
	v_mov_b64_e32 v[96:97], 0
	v_mov_b64_e32 v[98:99], 0
	v_mov_b64_e32 v[100:101], 0
	v_mov_b64_e32 v[102:103], 0
	v_mov_b64_e32 v[104:105], 0
	v_mov_b64_e32 v[106:107], 0
	v_mov_b64_e32 v[108:109], 0
	v_mov_b64_e32 v[110:111], 0
	v_mov_b64_e32 v[112:113], 0
	v_mov_b64_e32 v[114:115], 0
	v_mov_b64_e32 v[116:117], 0
	v_mov_b64_e32 v[118:119], 0
	v_mov_b64_e32 v[120:121], 0
	v_mov_b64_e32 v[122:123], 0
	v_mov_b64_e32 v[124:125], 0
	v_mov_b64_e32 v[126:127], 0

;     __device__ __forceinline__ bool zero_after(const Unit& u) const { return (u.pn / nN) == 2; }
; template <class Epi, class Sched, bool ALIGN_EPI = false, bool SP2 = false>
; __device__ __forceinline__ void gemm_phase(PG8_LAS unsigned char* lds, const Gemm g, const Sched& S, const Epi& E) {
;     ...
; #pragma unroll
;     for (int a = 0; a < 2; ++a)
; #pragma unroll
;         for (int b = 0; b < 2; ++b)
; #pragma unroll
;             for (int m = 0; m < 4; ++m)
; #pragma unroll
;                 for (int n = 0; n < 2; ++n) acc[a][b][m][n] = (f32x4){0.f, 0.f, 0.f, 0.f};
;     ...
;         if (E.zero_after(cur)) {
; #pragma unroll
;         for (int a = 0; a < 2; ++a)
; #pragma unroll
;             for (int b = 0; b < 2; ++b)
; #pragma unroll
;                 for (int m = 0; m < 4; ++m)
; #pragma unroll
;                     for (int n = 0; n < 2; ++n) acc[a][b][m][n] = (f32x4){0.f, 0.f, 0.f, 0.f};
;         }
.LBB0_849:
	v_mov_b32_e32 v123, 0
	s_andn2_b64 vcc, exec, s[16:17]
	v_mov_b32_e32 v122, v123
	v_mov_b32_e32 v121, v123
	v_mov_b32_e32 v120, v123
	v_mov_b32_e32 v127, v123
	v_mov_b32_e32 v126, v123
	v_mov_b32_e32 v125, v123
	v_mov_b32_e32 v124, v123
	v_mov_b32_e32 v111, v123
	v_mov_b32_e32 v110, v123
	v_mov_b32_e32 v109, v123
	v_mov_b32_e32 v108, v123
	v_mov_b32_e32 v107, v123
	v_mov_b32_e32 v106, v123
	v_mov_b32_e32 v105, v123
	v_mov_b32_e32 v104, v123
	v_mov_b32_e32 v95, v123
	v_mov_b32_e32 v94, v123
	v_mov_b32_e32 v93, v123
	v_mov_b32_e32 v92, v123
	v_mov_b32_e32 v91, v123
	v_mov_b32_e32 v90, v123
	v_mov_b32_e32 v89, v123
	v_mov_b32_e32 v88, v123
	v_mov_b32_e32 v79, v123
	v_mov_b32_e32 v78, v123
	v_mov_b32_e32 v77, v123
	v_mov_b32_e32 v76, v123
	v_mov_b32_e32 v75, v123
	v_mov_b32_e32 v74, v123
	v_mov_b32_e32 v73, v123
	v_mov_b32_e32 v72, v123
	v_mov_b32_e32 v119, v123
	v_mov_b32_e32 v118, v123
	v_mov_b32_e32 v117, v123
	v_mov_b32_e32 v116, v123
	v_mov_b32_e32 v115, v123
	v_mov_b32_e32 v114, v123
	v_mov_b32_e32 v113, v123
	v_mov_b32_e32 v112, v123
	v_mov_b32_e32 v103, v123
	v_mov_b32_e32 v102, v123
	v_mov_b32_e32 v101, v123
	v_mov_b32_e32 v100, v123
	v_mov_b32_e32 v99, v123
	v_mov_b32_e32 v98, v123
	v_mov_b32_e32 v97, v123
	v_mov_b32_e32 v96, v123
	v_mov_b32_e32 v87, v123
	v_mov_b32_e32 v86, v123
	v_mov_b32_e32 v85, v123
	v_mov_b32_e32 v84, v123
	v_mov_b32_e32 v83, v123
	v_mov_b32_e32 v82, v123
	v_mov_b32_e32 v81, v123
	v_mov_b32_e32 v80, v123
	v_mov_b32_e32 v71, v123
	v_mov_b32_e32 v70, v123
	v_mov_b32_e32 v69, v123
	v_mov_b32_e32 v68, v123
	v_mov_b32_e32 v67, v123
	v_mov_b32_e32 v66, v123
	v_mov_b32_e32 v65, v123
	v_mov_b32_e32 v64, v123
	v_mov_b32_e32 v63, v123
	v_mov_b32_e32 v62, v123
	v_mov_b32_e32 v61, v123
	v_mov_b32_e32 v60, v123
	v_mov_b32_e32 v59, v123
	v_mov_b32_e32 v58, v123
	v_mov_b32_e32 v57, v123
	v_mov_b32_e32 v56, v123
	v_mov_b32_e32 v47, v123
	v_mov_b32_e32 v46, v123
	v_mov_b32_e32 v45, v123
	v_mov_b32_e32 v44, v123
	v_mov_b32_e32 v43, v123
	v_mov_b32_e32 v42, v123
	v_mov_b32_e32 v41, v123
	v_mov_b32_e32 v40, v123
	v_mov_b32_e32 v31, v123
	v_mov_b32_e32 v30, v123
	v_mov_b32_e32 v29, v123
	v_mov_b32_e32 v28, v123
	v_mov_b32_e32 v27, v123
	v_mov_b32_e32 v26, v123
	v_mov_b32_e32 v25, v123
	v_mov_b32_e32 v24, v123
	v_mov_b32_e32 v15, v123
	v_mov_b32_e32 v14, v123
	v_mov_b32_e32 v13, v123
	v_mov_b32_e32 v12, v123
	v_mov_b32_e32 v11, v123
	v_mov_b32_e32 v10, v123
	v_mov_b32_e32 v9, v123
	v_mov_b32_e32 v8, v123
	v_mov_b32_e32 v55, v123
	v_mov_b32_e32 v54, v123
	v_mov_b32_e32 v53, v123
	v_mov_b32_e32 v52, v123
	v_mov_b32_e32 v51, v123
	v_mov_b32_e32 v50, v123
	v_mov_b32_e32 v49, v123
	v_mov_b32_e32 v48, v123
	v_mov_b32_e32 v39, v123
	v_mov_b32_e32 v38, v123
	v_mov_b32_e32 v37, v123
	v_mov_b32_e32 v36, v123
	v_mov_b32_e32 v35, v123
	v_mov_b32_e32 v34, v123
	v_mov_b32_e32 v33, v123
	v_mov_b32_e32 v32, v123
	v_mov_b32_e32 v23, v123
	v_mov_b32_e32 v22, v123
	v_mov_b32_e32 v21, v123
	v_mov_b32_e32 v20, v123
	v_mov_b32_e32 v19, v123
	v_mov_b32_e32 v18, v123
	v_mov_b32_e32 v17, v123
	v_mov_b32_e32 v16, v123
	v_mov_b32_e32 v7, v123
	v_mov_b32_e32 v6, v123
	v_mov_b32_e32 v5, v123
	v_mov_b32_e32 v4, v123
	v_mov_b32_e32 v3, v123
	v_mov_b32_e32 v2, v123
	v_mov_b32_e32 v1, v123
	v_mov_b32_e32 v0, v123
	s_cbranch_vccnz .LBB0_853
	s_add_u32 s22, s22, 0x80
	s_addc_u32 s23, s23, 0
	s_add_u32 s58, s24, 0x100
	s_addc_u32 s62, s25, 0
	s_mov_b32 s24, 0
	v_mov_b64_e32 v[0:1], 0
	v_mov_b64_e32 v[2:3], 0
	v_mov_b64_e32 v[4:5], 0
	v_mov_b64_e32 v[6:7], 0
	v_mov_b64_e32 v[8:9], 0
	v_mov_b64_e32 v[10:11], 0
	v_mov_b64_e32 v[12:13], 0
	v_mov_b64_e32 v[14:15], 0
	v_mov_b64_e32 v[16:17], 0
	v_mov_b64_e32 v[18:19], 0
	v_mov_b64_e32 v[20:21], 0
	v_mov_b64_e32 v[22:23], 0
	v_mov_b64_e32 v[24:25], 0
	v_mov_b64_e32 v[26:27], 0
	v_mov_b64_e32 v[28:29], 0
	v_mov_b64_e32 v[30:31], 0
	v_mov_b64_e32 v[32:33], 0
	v_mov_b64_e32 v[34:35], 0
	v_mov_b64_e32 v[36:37], 0
	v_mov_b64_e32 v[38:39], 0
	v_mov_b64_e32 v[40:41], 0
	v_mov_b64_e32 v[42:43], 0
	v_mov_b64_e32 v[44:45], 0
	v_mov_b64_e32 v[46:47], 0
	v_mov_b64_e32 v[48:49], 0
	v_mov_b64_e32 v[50:51], 0
	v_mov_b64_e32 v[52:53], 0
	v_mov_b64_e32 v[54:55], 0
	v_mov_b64_e32 v[56:57], 0
	v_mov_b64_e32 v[58:59], 0
	v_mov_b64_e32 v[60:61], 0
	v_mov_b64_e32 v[62:63], 0
	v_mov_b64_e32 v[64:65], 0
	v_mov_b64_e32 v[66:67], 0
	v_mov_b64_e32 v[68:69], 0
	v_mov_b64_e32 v[70:71], 0
	v_mov_b64_e32 v[72:73], 0
	v_mov_b64_e32 v[74:75], 0
	v_mov_b64_e32 v[76:77], 0
	v_mov_b64_e32 v[78:79], 0
	v_mov_b64_e32 v[80:81], 0
	v_mov_b64_e32 v[82:83], 0
	v_mov_b64_e32 v[84:85], 0
	v_mov_b64_e32 v[86:87], 0
	v_mov_b64_e32 v[88:89], 0
	v_mov_b64_e32 v[90:91], 0
	v_mov_b64_e32 v[92:93], 0
	v_mov_b64_e32 v[94:95], 0
	v_mov_b64_e32 v[96:97], 0
	v_mov_b64_e32 v[98:99], 0
	v_mov_b64_e32 v[100:101], 0
	v_mov_b64_e32 v[102:103], 0
	v_mov_b64_e32 v[104:105], 0
	v_mov_b64_e32 v[106:107], 0
	v_mov_b64_e32 v[108:109], 0
	v_mov_b64_e32 v[110:111], 0
	v_mov_b64_e32 v[112:113], 0
	v_mov_b64_e32 v[114:115], 0
	v_mov_b64_e32 v[116:117], 0
	v_mov_b64_e32 v[118:119], 0
	v_mov_b64_e32 v[120:121], 0
	v_mov_b64_e32 v[122:123], 0
	v_mov_b64_e32 v[124:125], 0
	v_mov_b64_e32 v[126:127], 0
